# lean K-loops: scalar pointer math moved into MFMA segments, kstep via inst offset, m0 hazard fixed, nop wait-states replaced by s_mov (P2/P4/P6)
# speedup vs baseline: 1.0006x; 1.0006x over previous
.LBB0_259:
	s_and_b32 s14, s10, 3
	s_mov_b64 s[10:11], 0x80
	s_add_i32 m0, s33, 0x18000
	v_lshl_add_u64 v[8:9], v[8:9], 0, s[10:11]
	s_lshl_b32 s15, s46, 13
	s_lshl_b32 s16, s14, 12
	s_waitcnt vmcnt(2)
	s_barrier
	global_load_lds_dwordx4 v[8:9], off
	v_lshl_add_u64 v[6:7], v[6:7], 0, s[10:11]
	s_add_i32 m0, s33, 0x1a000
	s_add_i32 s56, s33, 0x8000
	s_add_i32 s57, s33, 0xa000
	global_load_lds_dwordx4 v[6:7], off
	v_lshl_add_u64 v[2:3], v[2:3], 0, s[10:11]
	s_mov_b32 m0, s56
	s_add_u32 s12, s74, 0x100080
	global_load_lds_dwordx4 v[2:3], off
	v_lshl_add_u64 v[2:3], v[4:5], 0, s[10:11]
	s_mov_b32 m0, s57
	s_addc_u32 s13, s75, 0
	global_load_lds_dwordx4 v[2:3], off
	s_add_i32 m0, s33, 0x1c000
	v_lshl_add_u64 v[2:3], s[12:13], 0, v[134:135]
	global_load_lds_dwordx4 v[2:3], off
	v_lshl_add_u64 v[2:3], s[12:13], 0, v[130:131]
	s_add_i32 m0, s33, 0x1e000
	s_cmpk_lt_u32 s5, 0x100
	global_load_lds_dwordx4 v[2:3], off
	v_and_b32_e32 v3, 15, v13
	v_bfe_u32 v2, v13, 4, 2
	v_lshl_or_b32 v158, s46, 6, v3
	v_lshlrev_b32_e32 v6, 3, v2
	v_lshlrev_b32_e32 v2, 4, v2
	v_lshlrev_b32_e32 v4, 2, v13
	s_cselect_b64 s[46:47], -1, 0
	s_lshl_b32 s12, s14, 6
	v_lshl_or_b32 v3, v3, 6, v2
	v_and_b32_e32 v4, 32, v4
	v_or_b32_e32 v138, s12, v2
	s_sext_i32_i16 s79, s4
	v_bitop3_b32 v7, v3, s15, v4 bitop3:0xde
	v_bitop3_b32 v159, v3, s16, v4 bitop3:0xde
	v_lshl_add_u64 v[4:5], s[30:31], 0, v[138:139]
	s_mov_b64 s[4:5], 0x600000
	s_ashr_i32 s58, s97, 31
	v_lshl_add_u64 v[140:141], v[4:5], 0, s[4:5]
	s_mov_b64 s[4:5], 0xa00000
	v_lshl_add_u64 v[142:143], v[4:5], 0, s[4:5]
	s_add_u32 s4, s44, s12
	s_addc_u32 s5, s45, 0
	v_mov_b32_e32 v3, v139
	v_lshl_add_u64 v[144:145], s[4:5], 0, v[2:3]
	v_lshlrev_b32_e32 v2, 16, v15
	v_and_b32_e32 v2, 0xfffe0000, v2
	v_lshl_add_u32 v2, v14, 13, v2
	v_and_b32_e32 v3, 1, v15
	v_lshl_or_b32 v2, v3, 6, v2
	v_lshl_add_u32 v146, v16, 1, v2
	v_lshlrev_b32_e32 v2, 16, v10
	v_and_b32_e32 v2, 0xfffe0000, v2
	s_waitcnt vmcnt(6)
	v_lshl_add_u32 v2, v11, 13, v2
	v_and_b32_e32 v3, 1, v10
	v_lshl_or_b32 v2, v3, 6, v2
	s_add_i32 s59, 0, 0x10000
	s_add_i32 s60, 0, 0x14000
	v_lshl_or_b32 v160, s14, 5, v6
	v_mov_b32_e32 v147, v139
	v_lshl_add_u32 v148, v12, 1, v2
	v_mov_b32_e32 v149, v139
	v_mov_b64_e32 v[150:151], 0xc00
	v_mov_b64_e32 v[152:153], 0xbff
	v_add_u32_e32 v161, s59, v159
	v_add_u32_e32 v162, s60, v159
	v_add_u32_e32 v163, 0, v7
	s_mov_b32 s61, 0x80000
	s_mov_b32 s62, 0x90000
	s_mov_b64 s[48:49], 0xa0000
	s_mov_b32 s63, 0xa0000
	s_mov_b64 s[50:51], 0xb0000
	s_mov_b32 s78, 0xb0000
	v_add_u32_e32 v226, 0x18000, v159
	v_add_u32_e32 v227, 0x1c000, v159
	s_barrier
	s_branch .LBB0_262

.LBB0_265:
	ds_read_b128 v[154:157], v161
	ds_read_b128 v[164:167], v161 offset:1024
	ds_read_b128 v[168:171], v161 offset:2048
	ds_read_b128 v[172:175], v161 offset:3072
	ds_read_b128 v[176:179], v162
	ds_read_b128 v[180:183], v162 offset:1024
	ds_read_b128 v[184:187], v162 offset:2048
	ds_read_b128 v[188:191], v162 offset:3072
	ds_read_b128 v[192:195], v163
	ds_read_b128 v[196:199], v163 offset:1024
	ds_read_b128 v[200:203], v163 offset:2048
	ds_read_b128 v[204:207], v163 offset:3072
	ds_read_b128 v[208:211], v163 offset:4096
	ds_read_b128 v[212:215], v163 offset:5120
	ds_read_b128 v[216:219], v163 offset:6144
	ds_read_b128 v[220:223], v163 offset:7168
	s_add_i32 m0, s33, 0xc000
	s_mov_b32 s32, s32
	global_load_lds_dwordx4 v146, s[72:73]
	s_add_i32 m0, s33, 0xe000
	s_mov_b32 s32, s32
	global_load_lds_dwordx4 v148, s[72:73]
	s_waitcnt vmcnt(8)
	s_waitcnt lgkmcnt(0)
	s_barrier
	s_setprio 1
	v_mfma_f32_16x16x32_bf16 v[126:129], v[154:157], v[192:195], v[126:129]
	v_mfma_f32_16x16x32_bf16 v[122:125], v[168:171], v[192:195], v[122:125]
	v_mfma_f32_16x16x32_bf16 v[110:113], v[154:157], v[200:203], v[110:113]
	s_add_u32 s12, s72, 0xfff00080
	v_mfma_f32_16x16x32_bf16 v[106:109], v[168:171], v[200:203], v[106:109]
	s_addc_u32 s13, s73, -1
	v_mfma_f32_16x16x32_bf16 v[94:97], v[154:157], v[208:211], v[94:97]
	s_cmp_eq_u32 s83, 60
	v_mfma_f32_16x16x32_bf16 v[90:93], v[168:171], v[208:211], v[90:93]
	s_cselect_b32 s77, s55, s13
	v_mfma_f32_16x16x32_bf16 v[78:81], v[154:157], v[216:219], v[78:81]
	s_cselect_b32 s76, s71, s12
	v_mfma_f32_16x16x32_bf16 v[74:77], v[168:171], v[216:219], v[74:77]
	s_cselect_b32 s75, s53, s82
	v_mfma_f32_16x16x32_bf16 v[126:129], v[164:167], v[196:199], v[126:129]
	s_cselect_b32 s74, s80, s81
	v_mfma_f32_16x16x32_bf16 v[122:125], v[172:175], v[196:199], v[122:125]
	s_add_u32 s98, s74, 0x100000
	v_mfma_f32_16x16x32_bf16 v[110:113], v[164:167], v[204:207], v[110:113]
	s_addc_u32 s99, s75, 0
	v_mfma_f32_16x16x32_bf16 v[106:109], v[172:175], v[204:207], v[106:109]
	s_add_u32 s100, s76, 0x100000
	v_mfma_f32_16x16x32_bf16 v[94:97], v[164:167], v[212:215], v[94:97]
	s_addc_u32 s101, s77, 0
	v_mfma_f32_16x16x32_bf16 v[90:93], v[172:175], v[212:215], v[90:93]
	v_mfma_f32_16x16x32_bf16 v[78:81], v[164:167], v[220:223], v[78:81]
	v_mfma_f32_16x16x32_bf16 v[74:77], v[172:175], v[220:223], v[74:77]
	v_mfma_f32_16x16x32_bf16 v[118:121], v[176:179], v[192:195], v[118:121]
	v_mfma_f32_16x16x32_bf16 v[114:117], v[184:187], v[192:195], v[114:117]
	v_mfma_f32_16x16x32_bf16 v[102:105], v[176:179], v[200:203], v[102:105]
	v_mfma_f32_16x16x32_bf16 v[98:101], v[184:187], v[200:203], v[98:101]
	v_mfma_f32_16x16x32_bf16 v[86:89], v[176:179], v[208:211], v[86:89]
	v_mfma_f32_16x16x32_bf16 v[82:85], v[184:187], v[208:211], v[82:85]
	v_mfma_f32_16x16x32_bf16 v[70:73], v[176:179], v[216:219], v[70:73]
	v_mfma_f32_16x16x32_bf16 v[66:69], v[184:187], v[216:219], v[66:69]
	v_mfma_f32_16x16x32_bf16 v[118:121], v[180:183], v[196:199], v[118:121]
	v_mfma_f32_16x16x32_bf16 v[114:117], v[188:191], v[196:199], v[114:117]
	v_mfma_f32_16x16x32_bf16 v[102:105], v[180:183], v[204:207], v[102:105]
	v_mfma_f32_16x16x32_bf16 v[98:101], v[188:191], v[204:207], v[98:101]
	v_mfma_f32_16x16x32_bf16 v[86:89], v[180:183], v[212:215], v[86:89]
	v_mfma_f32_16x16x32_bf16 v[82:85], v[188:191], v[212:215], v[82:85]
	v_mfma_f32_16x16x32_bf16 v[70:73], v[180:183], v[220:223], v[70:73]
	v_mfma_f32_16x16x32_bf16 v[66:69], v[188:191], v[220:223], v[66:69]
	s_setprio 0
	s_barrier
	ds_read_b128 v[192:195], v163 offset:16384
	ds_read_b128 v[196:199], v163 offset:17408
	ds_read_b128 v[200:203], v163 offset:18432
	ds_read_b128 v[204:207], v163 offset:19456
	ds_read_b128 v[208:211], v163 offset:20480
	ds_read_b128 v[212:215], v163 offset:21504
	ds_read_b128 v[216:219], v163 offset:22528
	ds_read_b128 v[220:223], v163 offset:23552
	s_add_i32 m0, s33, 0x10000
	s_mov_b32 s32, s32
	global_load_lds_dwordx4 v134, s[74:75]
	s_add_i32 m0, s33, 0x12000
	s_mov_b32 s32, s32
	global_load_lds_dwordx4 v130, s[74:75]
	s_add_i32 m0, s33, 0x14000
	s_mov_b32 s32, s32
	global_load_lds_dwordx4 v134, s[98:99]
	s_add_i32 m0, s33, 0x16000
	s_mov_b32 s32, s32
	global_load_lds_dwordx4 v130, s[98:99]
	s_mov_b32 m0, s33
	s_mov_b32 s32, s32
	global_load_lds_dwordx4 v136, s[76:77]
	s_add_i32 m0, s33, 0x2000
	s_mov_b32 s32, s32
	global_load_lds_dwordx4 v132, s[76:77]
	s_waitcnt vmcnt(8)
	s_waitcnt lgkmcnt(0)
	s_barrier
	s_setprio 1
	v_mfma_f32_16x16x32_bf16 v[62:65], v[154:157], v[192:195], v[62:65]
	v_mfma_f32_16x16x32_bf16 v[58:61], v[168:171], v[192:195], v[58:61]
	v_mfma_f32_16x16x32_bf16 v[46:49], v[154:157], v[200:203], v[46:49]
	v_mfma_f32_16x16x32_bf16 v[42:45], v[168:171], v[200:203], v[42:45]
	v_mfma_f32_16x16x32_bf16 v[30:33], v[154:157], v[208:211], v[30:33]
	v_mfma_f32_16x16x32_bf16 v[26:29], v[168:171], v[208:211], v[26:29]
	v_mfma_f32_16x16x32_bf16 v[14:17], v[154:157], v[216:219], v[14:17]
	v_mfma_f32_16x16x32_bf16 v[10:13], v[168:171], v[216:219], v[10:13]
	v_mfma_f32_16x16x32_bf16 v[62:65], v[164:167], v[196:199], v[62:65]
	v_mfma_f32_16x16x32_bf16 v[58:61], v[172:175], v[196:199], v[58:61]
	v_mfma_f32_16x16x32_bf16 v[46:49], v[164:167], v[204:207], v[46:49]
	v_mfma_f32_16x16x32_bf16 v[42:45], v[172:175], v[204:207], v[42:45]
	v_mfma_f32_16x16x32_bf16 v[30:33], v[164:167], v[212:215], v[30:33]
	v_mfma_f32_16x16x32_bf16 v[26:29], v[172:175], v[212:215], v[26:29]
	v_mfma_f32_16x16x32_bf16 v[14:17], v[164:167], v[220:223], v[14:17]
	v_mfma_f32_16x16x32_bf16 v[10:13], v[172:175], v[220:223], v[10:13]
	v_mfma_f32_16x16x32_bf16 v[54:57], v[176:179], v[192:195], v[54:57]
	v_mfma_f32_16x16x32_bf16 v[50:53], v[184:187], v[192:195], v[50:53]
	v_mfma_f32_16x16x32_bf16 v[38:41], v[176:179], v[200:203], v[38:41]
	v_mfma_f32_16x16x32_bf16 v[34:37], v[184:187], v[200:203], v[34:37]
	v_mfma_f32_16x16x32_bf16 v[22:25], v[176:179], v[208:211], v[22:25]
	v_mfma_f32_16x16x32_bf16 v[18:21], v[184:187], v[208:211], v[18:21]
	v_mfma_f32_16x16x32_bf16 v[6:9], v[176:179], v[216:219], v[6:9]
	v_mfma_f32_16x16x32_bf16 v[2:5], v[184:187], v[216:219], v[2:5]
	v_mfma_f32_16x16x32_bf16 v[54:57], v[180:183], v[196:199], v[54:57]
	v_mfma_f32_16x16x32_bf16 v[50:53], v[188:191], v[196:199], v[50:53]
	v_mfma_f32_16x16x32_bf16 v[38:41], v[180:183], v[204:207], v[38:41]
	v_mfma_f32_16x16x32_bf16 v[34:37], v[188:191], v[204:207], v[34:37]
	v_mfma_f32_16x16x32_bf16 v[22:25], v[180:183], v[212:215], v[22:25]
	v_mfma_f32_16x16x32_bf16 v[18:21], v[188:191], v[212:215], v[18:21]
	v_mfma_f32_16x16x32_bf16 v[6:9], v[180:183], v[220:223], v[6:9]
	v_mfma_f32_16x16x32_bf16 v[2:5], v[188:191], v[220:223], v[2:5]
	s_setprio 0
	s_barrier
	ds_read_b128 v[154:157], v226
	ds_read_b128 v[164:167], v226 offset:1024
	ds_read_b128 v[168:171], v226 offset:2048
	ds_read_b128 v[172:175], v226 offset:3072
	ds_read_b128 v[176:179], v227
	ds_read_b128 v[180:183], v227 offset:1024
	ds_read_b128 v[184:187], v227 offset:2048
	ds_read_b128 v[188:191], v227 offset:3072
	ds_read_b128 v[192:195], v163 offset:32768
	ds_read_b128 v[196:199], v163 offset:33792
	ds_read_b128 v[200:203], v163 offset:34816
	ds_read_b128 v[204:207], v163 offset:35840
	ds_read_b128 v[208:211], v163 offset:36864
	ds_read_b128 v[212:215], v163 offset:37888
	ds_read_b128 v[216:219], v163 offset:38912
	ds_read_b128 v[220:223], v163 offset:39936
	s_add_i32 m0, s33, 0x4000
	s_mov_b32 s32, s32
	global_load_lds_dwordx4 v136, s[100:101]
	s_add_i32 m0, s33, 0x6000
	s_mov_b32 s32, s32
	global_load_lds_dwordx4 v132, s[100:101]
	s_waitcnt vmcnt(8)
	s_waitcnt lgkmcnt(0)
	s_barrier
	s_setprio 1
	v_mfma_f32_16x16x32_bf16 v[126:129], v[154:157], v[192:195], v[126:129]
	v_mfma_f32_16x16x32_bf16 v[122:125], v[168:171], v[192:195], v[122:125]
	v_mfma_f32_16x16x32_bf16 v[110:113], v[154:157], v[200:203], v[110:113]
	v_mfma_f32_16x16x32_bf16 v[106:109], v[168:171], v[200:203], v[106:109]
	v_mfma_f32_16x16x32_bf16 v[94:97], v[154:157], v[208:211], v[94:97]
	v_mfma_f32_16x16x32_bf16 v[90:93], v[168:171], v[208:211], v[90:93]
	v_mfma_f32_16x16x32_bf16 v[78:81], v[154:157], v[216:219], v[78:81]
	v_mfma_f32_16x16x32_bf16 v[74:77], v[168:171], v[216:219], v[74:77]
	v_mfma_f32_16x16x32_bf16 v[126:129], v[164:167], v[196:199], v[126:129]
	v_mfma_f32_16x16x32_bf16 v[122:125], v[172:175], v[196:199], v[122:125]
	v_mfma_f32_16x16x32_bf16 v[110:113], v[164:167], v[204:207], v[110:113]
	v_mfma_f32_16x16x32_bf16 v[106:109], v[172:175], v[204:207], v[106:109]
	v_mfma_f32_16x16x32_bf16 v[94:97], v[164:167], v[212:215], v[94:97]
	v_mfma_f32_16x16x32_bf16 v[90:93], v[172:175], v[212:215], v[90:93]
	v_mfma_f32_16x16x32_bf16 v[78:81], v[164:167], v[220:223], v[78:81]
	v_mfma_f32_16x16x32_bf16 v[74:77], v[172:175], v[220:223], v[74:77]
	v_mfma_f32_16x16x32_bf16 v[118:121], v[176:179], v[192:195], v[118:121]
	v_mfma_f32_16x16x32_bf16 v[114:117], v[184:187], v[192:195], v[114:117]
	v_mfma_f32_16x16x32_bf16 v[102:105], v[176:179], v[200:203], v[102:105]
	v_mfma_f32_16x16x32_bf16 v[98:101], v[184:187], v[200:203], v[98:101]
	v_mfma_f32_16x16x32_bf16 v[86:89], v[176:179], v[208:211], v[86:89]
	v_mfma_f32_16x16x32_bf16 v[82:85], v[184:187], v[208:211], v[82:85]
	v_mfma_f32_16x16x32_bf16 v[70:73], v[176:179], v[216:219], v[70:73]
	v_mfma_f32_16x16x32_bf16 v[66:69], v[184:187], v[216:219], v[66:69]
	v_mfma_f32_16x16x32_bf16 v[118:121], v[180:183], v[196:199], v[118:121]
	v_mfma_f32_16x16x32_bf16 v[114:117], v[188:191], v[196:199], v[114:117]
	v_mfma_f32_16x16x32_bf16 v[102:105], v[180:183], v[204:207], v[102:105]
	v_mfma_f32_16x16x32_bf16 v[98:101], v[188:191], v[204:207], v[98:101]
	v_mfma_f32_16x16x32_bf16 v[86:89], v[180:183], v[212:215], v[86:89]
	v_mfma_f32_16x16x32_bf16 v[82:85], v[188:191], v[212:215], v[82:85]
	v_mfma_f32_16x16x32_bf16 v[70:73], v[180:183], v[220:223], v[70:73]
	v_mfma_f32_16x16x32_bf16 v[66:69], v[188:191], v[220:223], v[66:69]
	s_setprio 0
	s_barrier
	ds_read_b128 v[192:195], v163 offset:49152
	ds_read_b128 v[196:199], v163 offset:50176
	ds_read_b128 v[200:203], v163 offset:51200
	ds_read_b128 v[204:207], v163 offset:52224
	ds_read_b128 v[208:211], v163 offset:53248
	ds_read_b128 v[212:215], v163 offset:54272
	ds_read_b128 v[216:219], v163 offset:55296
	ds_read_b128 v[220:223], v163 offset:56320
	s_add_i32 m0, s33, 0x17f80
	s_mov_b32 s32, s32
	global_load_lds_dwordx4 v134, s[74:75] offset:128
	s_add_i32 m0, s33, 0x19f80
	s_mov_b32 s32, s32
	global_load_lds_dwordx4 v130, s[74:75] offset:128
	s_add_i32 m0, s33, 0x1bf80
	s_mov_b32 s32, s32
	global_load_lds_dwordx4 v134, s[98:99] offset:128
	s_add_i32 m0, s33, 0x1df80
	s_mov_b32 s32, s32
	global_load_lds_dwordx4 v130, s[98:99] offset:128
	s_add_i32 m0, s33, 0x7f80
	s_mov_b32 s32, s32
	global_load_lds_dwordx4 v136, s[76:77] offset:128
	s_add_i32 m0, s33, 0x9f80
	s_mov_b32 s32, s32
	global_load_lds_dwordx4 v132, s[76:77] offset:128
	s_waitcnt vmcnt(8)
	s_waitcnt lgkmcnt(0)
	s_barrier
	s_setprio 1
	v_mfma_f32_16x16x32_bf16 v[62:65], v[154:157], v[192:195], v[62:65]
	v_mfma_f32_16x16x32_bf16 v[58:61], v[168:171], v[192:195], v[58:61]
	v_mfma_f32_16x16x32_bf16 v[46:49], v[154:157], v[200:203], v[46:49]
	v_mfma_f32_16x16x32_bf16 v[42:45], v[168:171], v[200:203], v[42:45]
	v_mfma_f32_16x16x32_bf16 v[30:33], v[154:157], v[208:211], v[30:33]
	v_mfma_f32_16x16x32_bf16 v[26:29], v[168:171], v[208:211], v[26:29]
	v_mfma_f32_16x16x32_bf16 v[14:17], v[154:157], v[216:219], v[14:17]
	v_mfma_f32_16x16x32_bf16 v[10:13], v[168:171], v[216:219], v[10:13]
	v_mfma_f32_16x16x32_bf16 v[62:65], v[164:167], v[196:199], v[62:65]
	v_mfma_f32_16x16x32_bf16 v[58:61], v[172:175], v[196:199], v[58:61]
	v_mfma_f32_16x16x32_bf16 v[46:49], v[164:167], v[204:207], v[46:49]
	v_mfma_f32_16x16x32_bf16 v[42:45], v[172:175], v[204:207], v[42:45]
	v_mfma_f32_16x16x32_bf16 v[30:33], v[164:167], v[212:215], v[30:33]
	v_mfma_f32_16x16x32_bf16 v[26:29], v[172:175], v[212:215], v[26:29]
	v_mfma_f32_16x16x32_bf16 v[14:17], v[164:167], v[220:223], v[14:17]
	v_mfma_f32_16x16x32_bf16 v[10:13], v[172:175], v[220:223], v[10:13]
	v_mfma_f32_16x16x32_bf16 v[54:57], v[176:179], v[192:195], v[54:57]
	v_mfma_f32_16x16x32_bf16 v[50:53], v[184:187], v[192:195], v[50:53]
	v_mfma_f32_16x16x32_bf16 v[38:41], v[176:179], v[200:203], v[38:41]
	v_mfma_f32_16x16x32_bf16 v[34:37], v[184:187], v[200:203], v[34:37]
	v_mfma_f32_16x16x32_bf16 v[22:25], v[176:179], v[208:211], v[22:25]
	v_mfma_f32_16x16x32_bf16 v[18:21], v[184:187], v[208:211], v[18:21]
	v_mfma_f32_16x16x32_bf16 v[6:9], v[176:179], v[216:219], v[6:9]
	v_mfma_f32_16x16x32_bf16 v[2:5], v[184:187], v[216:219], v[2:5]
	v_mfma_f32_16x16x32_bf16 v[54:57], v[180:183], v[196:199], v[54:57]
	v_mfma_f32_16x16x32_bf16 v[50:53], v[188:191], v[196:199], v[50:53]
	s_add_i32 s83, s83, 2
	v_mfma_f32_16x16x32_bf16 v[38:41], v[180:183], v[204:207], v[38:41]
	s_add_u32 s72, s72, 0x100
	v_mfma_f32_16x16x32_bf16 v[34:37], v[188:191], v[204:207], v[34:37]
	s_addc_u32 s73, s73, 0
	v_mfma_f32_16x16x32_bf16 v[22:25], v[180:183], v[212:215], v[22:25]
	s_add_u32 s81, s81, 0x100
	v_mfma_f32_16x16x32_bf16 v[18:21], v[188:191], v[212:215], v[18:21]
	s_addc_u32 s82, s82, 0
	v_mfma_f32_16x16x32_bf16 v[6:9], v[180:183], v[220:223], v[6:9]
	s_cmp_gt_u32 s83, 61
	v_mfma_f32_16x16x32_bf16 v[2:5], v[188:191], v[220:223], v[2:5]
	s_setprio 0
	s_barrier
	s_cbranch_scc0 .LBB0_265
	s_and_b64 vcc, exec, s[46:47]
	s_cbranch_vccz .LBB0_268
	s_barrier

.LBB0_500:
	s_mov_b64 s[18:19], 0x80
	s_and_b32 s33, s4, 3
	s_add_i32 m0, s1, 0x18000
	v_lshl_add_u64 v[8:9], v[8:9], 0, s[18:19]
	s_lshl_b32 s4, s5, 13
	s_lshl_b32 s21, s33, 12
	s_waitcnt vmcnt(2)
	s_barrier
	global_load_lds_dwordx4 v[8:9], off
	v_lshl_add_u64 v[6:7], v[6:7], 0, s[18:19]
	s_add_i32 m0, s1, 0x1a000
	s_add_i32 s35, s1, 0x8000
	s_add_i32 s39, s1, 0xa000
	global_load_lds_dwordx4 v[6:7], off
	v_lshl_add_u64 v[2:3], v[2:3], 0, s[18:19]
	s_mov_b32 m0, s35
	s_add_u32 s6, s52, 0x100080
	global_load_lds_dwordx4 v[2:3], off
	v_lshl_add_u64 v[2:3], v[4:5], 0, s[18:19]
	s_mov_b32 m0, s39
	s_addc_u32 s7, s53, 0
	global_load_lds_dwordx4 v[2:3], off
	s_add_i32 m0, s1, 0x1c000
	v_lshl_add_u64 v[2:3], s[6:7], 0, v[132:133]
	global_load_lds_dwordx4 v[2:3], off
	v_lshl_add_u64 v[2:3], s[6:7], 0, v[136:137]
	s_add_i32 m0, s1, 0x1e000
	s_cmpk_lt_u32 s20, 0x100
	global_load_lds_dwordx4 v[2:3], off
	v_bfe_u32 v2, v10, 4, 2
	v_and_b32_e32 v3, 15, v10
	v_lshlrev_b32_e32 v5, 4, v2
	v_lshl_or_b32 v1, s5, 6, v3
	v_lshl_or_b32 v3, v3, 6, v5
	v_lshlrev_b32_e32 v5, 2, v10
	v_and_b32_e32 v5, 32, v5
	v_lshlrev_b32_e32 v4, 3, v2
	v_bitop3_b32 v6, v3, s4, v5 bitop3:0xde
	v_cmp_eq_u32_e64 s[4:5], 0, v2
	v_lshlrev_b32_e32 v2, 16, v11
	v_and_b32_e32 v2, 0xfffe0000, v2
	v_bitop3_b32 v150, v3, s21, v5 bitop3:0xde
	v_lshl_add_u32 v2, v12, 13, v2
	v_and_b32_e32 v3, 1, v11
	v_lshl_or_b32 v2, v3, 6, v2
	v_lshl_add_u32 v138, v13, 1, v2
	v_lshlrev_b32_e32 v2, 16, v14
	v_and_b32_e32 v2, 0xfffe0000, v2
	s_waitcnt vmcnt(6)
	v_lshl_add_u32 v2, v15, 13, v2
	v_and_b32_e32 v3, 1, v14
	s_cselect_b64 s[20:21], -1, 0
	v_lshl_or_b32 v2, v3, 6, v2
	s_add_i32 s56, 0, 0x10000
	s_add_i32 s57, 0, 0x14000
	v_lshl_or_b32 v151, s33, 5, v4
	s_ashr_i32 s40, s97, 31
	s_ashr_i32 s41, s2, 31
	v_mov_b32_e32 v139, v133
	v_lshl_add_u32 v140, v16, 1, v2
	v_mov_b32_e32 v141, v133
	v_mov_b64_e32 v[142:143], 0x400
	v_mov_b64_e32 v[144:145], 0x3ff
	v_add_u32_e32 v152, s56, v150
	v_add_u32_e32 v153, s57, v150
	v_add_u32_e32 v154, 0, v6
	s_mov_b32 s58, 0
	v_add_u32_e32 v226, 0x18000, v150
	v_add_u32_e32 v227, 0x1c000, v150
	s_barrier
	s_branch .LBB0_503

.LBB0_510:
	ds_read_b128 v[146:149], v152
	ds_read_b128 v[156:159], v152 offset:1024
	ds_read_b128 v[160:163], v152 offset:2048
	ds_read_b128 v[164:167], v152 offset:3072
	ds_read_b128 v[168:171], v153
	ds_read_b128 v[172:175], v153 offset:1024
	ds_read_b128 v[176:179], v153 offset:2048
	ds_read_b128 v[180:183], v153 offset:3072
	ds_read_b128 v[184:187], v154
	ds_read_b128 v[188:191], v154 offset:1024
	ds_read_b128 v[192:195], v154 offset:2048
	ds_read_b128 v[196:199], v154 offset:3072
	ds_read_b128 v[206:209], v154 offset:4096
	ds_read_b128 v[210:213], v154 offset:5120
	ds_read_b128 v[214:217], v154 offset:6144
	ds_read_b128 v[218:221], v154 offset:7168
	s_add_i32 m0, s1, 0xc000
	s_mov_b32 s32, s32
	global_load_lds_dwordx4 v138, s[52:53]
	s_add_i32 m0, s1, 0xe000
	s_mov_b32 s32, s32
	global_load_lds_dwordx4 v140, s[52:53]
	s_waitcnt vmcnt(8)
	s_waitcnt lgkmcnt(0)
	s_barrier
	s_setprio 1
	v_mfma_f32_16x16x32_bf16 v[126:129], v[146:149], v[184:187], v[126:129]
	v_mfma_f32_16x16x32_bf16 v[122:125], v[160:163], v[184:187], v[122:125]
	v_mfma_f32_16x16x32_bf16 v[110:113], v[146:149], v[192:195], v[110:113]
	s_add_u32 s34, s52, 0xfff00080
	v_mfma_f32_16x16x32_bf16 v[106:109], v[160:163], v[192:195], v[106:109]
	s_addc_u32 s36, s53, -1
	v_mfma_f32_16x16x32_bf16 v[94:97], v[146:149], v[206:209], v[94:97]
	s_cmp_eq_u32 s62, 60
	v_mfma_f32_16x16x32_bf16 v[90:93], v[160:163], v[206:209], v[90:93]
	s_cselect_b32 s67, s45, s36
	v_mfma_f32_16x16x32_bf16 v[78:81], v[146:149], v[214:217], v[78:81]
	s_cselect_b32 s66, s51, s34
	v_mfma_f32_16x16x32_bf16 v[74:77], v[160:163], v[214:217], v[74:77]
	s_cselect_b32 s55, s23, s61
	v_mfma_f32_16x16x32_bf16 v[126:129], v[156:159], v[188:191], v[126:129]
	s_cselect_b32 s54, s59, s60
	v_mfma_f32_16x16x32_bf16 v[122:125], v[164:167], v[188:191], v[122:125]
	s_add_u32 s98, s54, 0x100000
	v_mfma_f32_16x16x32_bf16 v[110:113], v[156:159], v[196:199], v[110:113]
	s_addc_u32 s99, s55, 0
	v_mfma_f32_16x16x32_bf16 v[106:109], v[164:167], v[196:199], v[106:109]
	s_add_u32 s100, s66, 0x100000
	v_mfma_f32_16x16x32_bf16 v[94:97], v[156:159], v[210:213], v[94:97]
	s_addc_u32 s101, s67, 0
	v_mfma_f32_16x16x32_bf16 v[90:93], v[164:167], v[210:213], v[90:93]
	v_mfma_f32_16x16x32_bf16 v[78:81], v[156:159], v[218:221], v[78:81]
	v_mfma_f32_16x16x32_bf16 v[74:77], v[164:167], v[218:221], v[74:77]
	v_mfma_f32_16x16x32_bf16 v[118:121], v[168:171], v[184:187], v[118:121]
	v_mfma_f32_16x16x32_bf16 v[114:117], v[176:179], v[184:187], v[114:117]
	v_mfma_f32_16x16x32_bf16 v[102:105], v[168:171], v[192:195], v[102:105]
	v_mfma_f32_16x16x32_bf16 v[98:101], v[176:179], v[192:195], v[98:101]
	v_mfma_f32_16x16x32_bf16 v[86:89], v[168:171], v[206:209], v[86:89]
	v_mfma_f32_16x16x32_bf16 v[82:85], v[176:179], v[206:209], v[82:85]
	v_mfma_f32_16x16x32_bf16 v[70:73], v[168:171], v[214:217], v[70:73]
	v_mfma_f32_16x16x32_bf16 v[66:69], v[176:179], v[214:217], v[66:69]
	v_mfma_f32_16x16x32_bf16 v[118:121], v[172:175], v[188:191], v[118:121]
	v_mfma_f32_16x16x32_bf16 v[114:117], v[180:183], v[188:191], v[114:117]
	v_mfma_f32_16x16x32_bf16 v[102:105], v[172:175], v[196:199], v[102:105]
	v_mfma_f32_16x16x32_bf16 v[98:101], v[180:183], v[196:199], v[98:101]
	v_mfma_f32_16x16x32_bf16 v[86:89], v[172:175], v[210:213], v[86:89]
	v_mfma_f32_16x16x32_bf16 v[82:85], v[180:183], v[210:213], v[82:85]
	v_mfma_f32_16x16x32_bf16 v[70:73], v[172:175], v[218:221], v[70:73]
	v_mfma_f32_16x16x32_bf16 v[66:69], v[180:183], v[218:221], v[66:69]
	s_setprio 0
	s_barrier
	ds_read_b128 v[184:187], v154 offset:16384
	ds_read_b128 v[188:191], v154 offset:17408
	ds_read_b128 v[192:195], v154 offset:18432
	ds_read_b128 v[196:199], v154 offset:19456
	ds_read_b128 v[206:209], v154 offset:20480
	ds_read_b128 v[210:213], v154 offset:21504
	ds_read_b128 v[214:217], v154 offset:22528
	ds_read_b128 v[218:221], v154 offset:23552
	s_add_i32 m0, s1, 0x10000
	s_mov_b32 s32, s32
	global_load_lds_dwordx4 v132, s[54:55]
	s_add_i32 m0, s1, 0x12000
	s_mov_b32 s32, s32
	global_load_lds_dwordx4 v136, s[54:55]
	s_add_i32 m0, s1, 0x14000
	s_mov_b32 s32, s32
	global_load_lds_dwordx4 v132, s[98:99]
	s_add_i32 m0, s1, 0x16000
	s_mov_b32 s32, s32
	global_load_lds_dwordx4 v136, s[98:99]
	s_mov_b32 m0, s1
	s_mov_b32 s32, s32
	global_load_lds_dwordx4 v130, s[66:67]
	s_add_i32 m0, s1, 0x2000
	s_mov_b32 s32, s32
	global_load_lds_dwordx4 v134, s[66:67]
	s_waitcnt vmcnt(8)
	s_waitcnt lgkmcnt(0)
	s_barrier
	s_setprio 1
	v_mfma_f32_16x16x32_bf16 v[62:65], v[146:149], v[184:187], v[62:65]
	v_mfma_f32_16x16x32_bf16 v[58:61], v[160:163], v[184:187], v[58:61]
	v_mfma_f32_16x16x32_bf16 v[46:49], v[146:149], v[192:195], v[46:49]
	v_mfma_f32_16x16x32_bf16 v[42:45], v[160:163], v[192:195], v[42:45]
	v_mfma_f32_16x16x32_bf16 v[30:33], v[146:149], v[206:209], v[30:33]
	v_mfma_f32_16x16x32_bf16 v[26:29], v[160:163], v[206:209], v[26:29]
	v_mfma_f32_16x16x32_bf16 v[14:17], v[146:149], v[214:217], v[14:17]
	v_mfma_f32_16x16x32_bf16 v[10:13], v[160:163], v[214:217], v[10:13]
	v_mfma_f32_16x16x32_bf16 v[62:65], v[156:159], v[188:191], v[62:65]
	v_mfma_f32_16x16x32_bf16 v[58:61], v[164:167], v[188:191], v[58:61]
	v_mfma_f32_16x16x32_bf16 v[46:49], v[156:159], v[196:199], v[46:49]
	v_mfma_f32_16x16x32_bf16 v[42:45], v[164:167], v[196:199], v[42:45]
	v_mfma_f32_16x16x32_bf16 v[30:33], v[156:159], v[210:213], v[30:33]
	v_mfma_f32_16x16x32_bf16 v[26:29], v[164:167], v[210:213], v[26:29]
	v_mfma_f32_16x16x32_bf16 v[14:17], v[156:159], v[218:221], v[14:17]
	v_mfma_f32_16x16x32_bf16 v[10:13], v[164:167], v[218:221], v[10:13]
	v_mfma_f32_16x16x32_bf16 v[54:57], v[168:171], v[184:187], v[54:57]
	v_mfma_f32_16x16x32_bf16 v[50:53], v[176:179], v[184:187], v[50:53]
	v_mfma_f32_16x16x32_bf16 v[38:41], v[168:171], v[192:195], v[38:41]
	v_mfma_f32_16x16x32_bf16 v[34:37], v[176:179], v[192:195], v[34:37]
	v_mfma_f32_16x16x32_bf16 v[22:25], v[168:171], v[206:209], v[22:25]
	v_mfma_f32_16x16x32_bf16 v[18:21], v[176:179], v[206:209], v[18:21]
	v_mfma_f32_16x16x32_bf16 v[6:9], v[168:171], v[214:217], v[6:9]
	v_mfma_f32_16x16x32_bf16 v[2:5], v[176:179], v[214:217], v[2:5]
	v_mfma_f32_16x16x32_bf16 v[54:57], v[172:175], v[188:191], v[54:57]
	v_mfma_f32_16x16x32_bf16 v[50:53], v[180:183], v[188:191], v[50:53]
	v_mfma_f32_16x16x32_bf16 v[38:41], v[172:175], v[196:199], v[38:41]
	v_mfma_f32_16x16x32_bf16 v[34:37], v[180:183], v[196:199], v[34:37]
	v_mfma_f32_16x16x32_bf16 v[22:25], v[172:175], v[210:213], v[22:25]
	v_mfma_f32_16x16x32_bf16 v[18:21], v[180:183], v[210:213], v[18:21]
	v_mfma_f32_16x16x32_bf16 v[6:9], v[172:175], v[218:221], v[6:9]
	v_mfma_f32_16x16x32_bf16 v[2:5], v[180:183], v[218:221], v[2:5]
	s_setprio 0
	s_barrier
	ds_read_b128 v[146:149], v226
	ds_read_b128 v[156:159], v226 offset:1024
	ds_read_b128 v[160:163], v226 offset:2048
	ds_read_b128 v[164:167], v226 offset:3072
	ds_read_b128 v[168:171], v227
	ds_read_b128 v[172:175], v227 offset:1024
	ds_read_b128 v[176:179], v227 offset:2048
	ds_read_b128 v[180:183], v227 offset:3072
	ds_read_b128 v[184:187], v154 offset:32768
	ds_read_b128 v[188:191], v154 offset:33792
	ds_read_b128 v[192:195], v154 offset:34816
	ds_read_b128 v[196:199], v154 offset:35840
	ds_read_b128 v[206:209], v154 offset:36864
	ds_read_b128 v[210:213], v154 offset:37888
	ds_read_b128 v[214:217], v154 offset:38912
	ds_read_b128 v[218:221], v154 offset:39936
	s_add_i32 m0, s1, 0x4000
	s_mov_b32 s32, s32
	global_load_lds_dwordx4 v130, s[100:101]
	s_add_i32 m0, s1, 0x6000
	s_mov_b32 s32, s32
	global_load_lds_dwordx4 v134, s[100:101]
	s_waitcnt vmcnt(8)
	s_waitcnt lgkmcnt(0)
	s_barrier
	s_setprio 1
	v_mfma_f32_16x16x32_bf16 v[126:129], v[146:149], v[184:187], v[126:129]
	v_mfma_f32_16x16x32_bf16 v[122:125], v[160:163], v[184:187], v[122:125]
	v_mfma_f32_16x16x32_bf16 v[110:113], v[146:149], v[192:195], v[110:113]
	v_mfma_f32_16x16x32_bf16 v[106:109], v[160:163], v[192:195], v[106:109]
	v_mfma_f32_16x16x32_bf16 v[94:97], v[146:149], v[206:209], v[94:97]
	v_mfma_f32_16x16x32_bf16 v[90:93], v[160:163], v[206:209], v[90:93]
	v_mfma_f32_16x16x32_bf16 v[78:81], v[146:149], v[214:217], v[78:81]
	v_mfma_f32_16x16x32_bf16 v[74:77], v[160:163], v[214:217], v[74:77]
	v_mfma_f32_16x16x32_bf16 v[126:129], v[156:159], v[188:191], v[126:129]
	v_mfma_f32_16x16x32_bf16 v[122:125], v[164:167], v[188:191], v[122:125]
	v_mfma_f32_16x16x32_bf16 v[110:113], v[156:159], v[196:199], v[110:113]
	v_mfma_f32_16x16x32_bf16 v[106:109], v[164:167], v[196:199], v[106:109]
	v_mfma_f32_16x16x32_bf16 v[94:97], v[156:159], v[210:213], v[94:97]
	v_mfma_f32_16x16x32_bf16 v[90:93], v[164:167], v[210:213], v[90:93]
	v_mfma_f32_16x16x32_bf16 v[78:81], v[156:159], v[218:221], v[78:81]
	v_mfma_f32_16x16x32_bf16 v[74:77], v[164:167], v[218:221], v[74:77]
	v_mfma_f32_16x16x32_bf16 v[118:121], v[168:171], v[184:187], v[118:121]
	v_mfma_f32_16x16x32_bf16 v[114:117], v[176:179], v[184:187], v[114:117]
	v_mfma_f32_16x16x32_bf16 v[102:105], v[168:171], v[192:195], v[102:105]
	v_mfma_f32_16x16x32_bf16 v[98:101], v[176:179], v[192:195], v[98:101]
	v_mfma_f32_16x16x32_bf16 v[86:89], v[168:171], v[206:209], v[86:89]
	v_mfma_f32_16x16x32_bf16 v[82:85], v[176:179], v[206:209], v[82:85]
	v_mfma_f32_16x16x32_bf16 v[70:73], v[168:171], v[214:217], v[70:73]
	v_mfma_f32_16x16x32_bf16 v[66:69], v[176:179], v[214:217], v[66:69]
	v_mfma_f32_16x16x32_bf16 v[118:121], v[172:175], v[188:191], v[118:121]
	v_mfma_f32_16x16x32_bf16 v[114:117], v[180:183], v[188:191], v[114:117]
	v_mfma_f32_16x16x32_bf16 v[102:105], v[172:175], v[196:199], v[102:105]
	v_mfma_f32_16x16x32_bf16 v[98:101], v[180:183], v[196:199], v[98:101]
	v_mfma_f32_16x16x32_bf16 v[86:89], v[172:175], v[210:213], v[86:89]
	v_mfma_f32_16x16x32_bf16 v[82:85], v[180:183], v[210:213], v[82:85]
	v_mfma_f32_16x16x32_bf16 v[70:73], v[172:175], v[218:221], v[70:73]
	v_mfma_f32_16x16x32_bf16 v[66:69], v[180:183], v[218:221], v[66:69]
	s_setprio 0
	s_barrier
	ds_read_b128 v[184:187], v154 offset:49152
	ds_read_b128 v[188:191], v154 offset:50176
	ds_read_b128 v[192:195], v154 offset:51200
	ds_read_b128 v[196:199], v154 offset:52224
	ds_read_b128 v[206:209], v154 offset:53248
	ds_read_b128 v[210:213], v154 offset:54272
	ds_read_b128 v[214:217], v154 offset:55296
	ds_read_b128 v[218:221], v154 offset:56320
	s_add_i32 m0, s1, 0x17f80
	s_mov_b32 s32, s32
	global_load_lds_dwordx4 v132, s[54:55] offset:128
	s_add_i32 m0, s1, 0x19f80
	s_mov_b32 s32, s32
	global_load_lds_dwordx4 v136, s[54:55] offset:128
	s_add_i32 m0, s1, 0x1bf80
	s_mov_b32 s32, s32
	global_load_lds_dwordx4 v132, s[98:99] offset:128
	s_add_i32 m0, s1, 0x1df80
	s_mov_b32 s32, s32
	global_load_lds_dwordx4 v136, s[98:99] offset:128
	s_add_i32 m0, s1, 0x7f80
	s_mov_b32 s32, s32
	global_load_lds_dwordx4 v130, s[66:67] offset:128
	s_add_i32 m0, s1, 0x9f80
	s_mov_b32 s32, s32
	global_load_lds_dwordx4 v134, s[66:67] offset:128
	s_waitcnt vmcnt(8)
	s_waitcnt lgkmcnt(0)
	s_barrier
	s_setprio 1
	v_mfma_f32_16x16x32_bf16 v[62:65], v[146:149], v[184:187], v[62:65]
	v_mfma_f32_16x16x32_bf16 v[58:61], v[160:163], v[184:187], v[58:61]
	v_mfma_f32_16x16x32_bf16 v[46:49], v[146:149], v[192:195], v[46:49]
	v_mfma_f32_16x16x32_bf16 v[42:45], v[160:163], v[192:195], v[42:45]
	v_mfma_f32_16x16x32_bf16 v[30:33], v[146:149], v[206:209], v[30:33]
	v_mfma_f32_16x16x32_bf16 v[26:29], v[160:163], v[206:209], v[26:29]
	v_mfma_f32_16x16x32_bf16 v[14:17], v[146:149], v[214:217], v[14:17]
	v_mfma_f32_16x16x32_bf16 v[10:13], v[160:163], v[214:217], v[10:13]
	v_mfma_f32_16x16x32_bf16 v[62:65], v[156:159], v[188:191], v[62:65]
	v_mfma_f32_16x16x32_bf16 v[58:61], v[164:167], v[188:191], v[58:61]
	v_mfma_f32_16x16x32_bf16 v[46:49], v[156:159], v[196:199], v[46:49]
	v_mfma_f32_16x16x32_bf16 v[42:45], v[164:167], v[196:199], v[42:45]
	v_mfma_f32_16x16x32_bf16 v[30:33], v[156:159], v[210:213], v[30:33]
	v_mfma_f32_16x16x32_bf16 v[26:29], v[164:167], v[210:213], v[26:29]
	v_mfma_f32_16x16x32_bf16 v[14:17], v[156:159], v[218:221], v[14:17]
	v_mfma_f32_16x16x32_bf16 v[10:13], v[164:167], v[218:221], v[10:13]
	v_mfma_f32_16x16x32_bf16 v[54:57], v[168:171], v[184:187], v[54:57]
	v_mfma_f32_16x16x32_bf16 v[50:53], v[176:179], v[184:187], v[50:53]
	v_mfma_f32_16x16x32_bf16 v[38:41], v[168:171], v[192:195], v[38:41]
	v_mfma_f32_16x16x32_bf16 v[34:37], v[176:179], v[192:195], v[34:37]
	v_mfma_f32_16x16x32_bf16 v[22:25], v[168:171], v[206:209], v[22:25]
	v_mfma_f32_16x16x32_bf16 v[18:21], v[176:179], v[206:209], v[18:21]
	v_mfma_f32_16x16x32_bf16 v[6:9], v[168:171], v[214:217], v[6:9]
	v_mfma_f32_16x16x32_bf16 v[2:5], v[176:179], v[214:217], v[2:5]
	v_mfma_f32_16x16x32_bf16 v[54:57], v[172:175], v[188:191], v[54:57]
	v_mfma_f32_16x16x32_bf16 v[50:53], v[180:183], v[188:191], v[50:53]
	s_add_i32 s62, s62, 2
	v_mfma_f32_16x16x32_bf16 v[38:41], v[172:175], v[196:199], v[38:41]
	s_add_u32 s60, s60, 0x100
	v_mfma_f32_16x16x32_bf16 v[34:37], v[180:183], v[196:199], v[34:37]
	s_addc_u32 s61, s61, 0
	v_mfma_f32_16x16x32_bf16 v[22:25], v[172:175], v[210:213], v[22:25]
	s_add_u32 s52, s52, 0x100
	v_mfma_f32_16x16x32_bf16 v[18:21], v[180:183], v[210:213], v[18:21]
	s_addc_u32 s53, s53, 0
	v_mfma_f32_16x16x32_bf16 v[6:9], v[172:175], v[218:221], v[6:9]
	s_cmp_gt_u32 s62, 61
	v_mfma_f32_16x16x32_bf16 v[2:5], v[180:183], v[218:221], v[2:5]
	s_setprio 0
	s_barrier
	s_cbranch_scc0 .LBB0_510
	s_and_b64 vcc, exec, s[20:21]
	s_cbranch_vccz .LBB0_513
	s_barrier

.LBB0_645:
	s_mov_b64 s[22:23], 0x80
	s_and_b32 s6, s0, 3
	s_add_i32 m0, s39, 0x18000
	v_lshl_add_u64 v[8:9], v[8:9], 0, s[22:23]
	s_lshl_b32 s7, s8, 13
	s_lshl_b32 s13, s6, 5
	s_lshl_b32 s9, s6, 12
	s_waitcnt vmcnt(2)
	s_barrier
	global_load_lds_dwordx4 v[8:9], off
	v_lshl_add_u64 v[6:7], v[6:7], 0, s[22:23]
	s_add_i32 m0, s39, 0x1a000
	s_add_i32 s33, s39, 0x8000
	s_add_i32 s0, s39, 0xa000
	global_load_lds_dwordx4 v[6:7], off
	v_lshl_add_u64 v[2:3], v[2:3], 0, s[22:23]
	s_mov_b32 m0, s33
	s_add_u32 s4, s90, 0x100080
	global_load_lds_dwordx4 v[2:3], off
	v_lshl_add_u64 v[2:3], v[4:5], 0, s[22:23]
	s_mov_b32 m0, s0
	s_addc_u32 s5, s91, 0
	global_load_lds_dwordx4 v[2:3], off
	s_add_i32 m0, s39, 0x1c000
	v_lshl_add_u64 v[2:3], s[4:5], 0, v[172:173]
	global_load_lds_dwordx4 v[2:3], off
	v_lshl_add_u64 v[2:3], s[4:5], 0, v[176:177]
	s_add_i32 m0, s39, 0x1e000
	s_cmpk_lt_u32 s1, 0x100
	global_load_lds_dwordx4 v[2:3], off
	s_cselect_b64 s[36:37], -1, 0
	s_lshl_b32 s34, s8, 11
	s_lshl_b32 s56, s6, 9
	v_and_b32_e32 v20, 15, v1
	s_cmp_gt_i32 s8, 0
	v_cmp_eq_u32_e32 vcc, 0, v20
	s_cselect_b64 s[40:41], -1, 0
	s_and_b64 s[44:45], vcc, s[40:41]
	s_or_b32 s57, s56, 0xfffff800
	s_cmp_eq_u32 s8, 3
	v_cmp_eq_u32_e64 s[4:5], 15, v20
	s_cselect_b64 s[46:47], -1, 0
	s_and_b64 s[46:47], s[4:5], s[46:47]
	s_add_i32 s1, s8, 2
	s_cmp_gt_i32 s8, -2
	s_cselect_b64 s[54:55], -1, 0
	s_and_b64 s[48:49], vcc, s[54:55]
	s_lshl_b32 s66, s1, 11
	v_bfe_u32 v21, v1, 4, 2
	v_cmp_ne_u32_e64 s[10:11], 0, v20
	s_cmp_eq_u32 s1, 3
	v_readlane_b32 s68, v238, 32
	v_lshlrev_b32_e32 v206, 4, v21
	v_lshlrev_b32_e32 v22, 2, v20
	s_cselect_b64 s[50:51], -1, 0
	s_or_b64 s[52:53], s[10:11], s[40:41]
	s_or_b64 s[54:55], s[10:11], s[54:55]
	s_add_i32 s10, 0, 0x20000
	v_readlane_b32 s74, v238, 38
	v_readlane_b32 s75, v238, 39
	v_lshlrev_b32_e32 v1, 3, v21
	v_lshl_or_b32 v21, v20, 6, v206
	v_and_b32_e32 v23, 32, v22
	v_or_b32_e32 v3, s8, v20
	s_add_i32 s41, s10, s34
	v_readlane_b32 s72, v238, 36
	v_readlane_b32 s73, v238, 37
	s_mov_b64 s[78:79], s[74:75]
	v_bitop3_b32 v2, v21, s7, v23 bitop3:0xde
	v_cmp_eq_u32_e64 s[6:7], 0, v3
	v_or_b32_e32 v3, s1, v20
	s_and_b64 s[50:51], s[4:5], s[50:51]
	s_or_b32 s67, s56, 0xfffff900
	s_ashr_i32 s1, s97, 31
	s_ashr_i32 s60, s2, 31
	s_add_i32 s61, s41, s56
	s_mov_b64 s[76:77], s[72:73]
	s_add_u32 s64, s76, 0xac00
	s_addc_u32 s65, s77, 0
	v_readlane_b32 s69, v238, 33
	s_add_u32 s68, s76, 0x15800
	v_readlane_b32 s70, v238, 34
	s_addc_u32 s69, s77, 0
	v_readlane_b32 s71, v238, 35
	s_add_u32 s70, s76, 0x20400
	v_and_b32_e32 v4, 1, v10
	v_bitop3_b32 v207, v21, s9, v23 bitop3:0xde
	v_lshl_or_b32 v208, s8, 6, v22
	v_cmp_eq_u32_e64 s[8:9], 0, v3
	s_addc_u32 s71, s77, 0
	v_add3_u32 v3, v12, v13, v14
	v_lshlrev_b32_e32 v4, 6, v4
	s_add_u32 s72, s76, 0x2b000
	v_lshl_or_b32 v3, v3, 13, v4
	v_and_b32_e32 v4, 1, v15
	s_addc_u32 s73, s77, 0
	v_lshl_add_u32 v178, v11, 1, v3
	v_add3_u32 v3, v17, v18, v19
	v_lshlrev_b32_e32 v4, 6, v4
	s_mov_b64 s[58:59], 0x100080
	s_add_u32 s74, s76, 0x35c00
	v_lshl_or_b32 v3, v3, 13, v4
	s_waitcnt vmcnt(6)
	s_addc_u32 s75, s77, 0
	s_add_i32 s56, s10, s66
	v_lshl_add_u64 v[180:181], v[178:179], 0, s[58:59]
	v_lshl_add_u32 v178, v16, 1, v3
	s_add_i32 s96, s41, s57
	s_add_i32 s40, s56, s57
	v_lshl_add_u64 v[182:183], v[178:179], 0, s[58:59]
	s_add_i32 s57, 0, 0x10000
	s_add_i32 s58, 0, 0x14000
	s_add_i32 s41, s41, s67
	s_add_i32 s56, s56, s67
	v_or_b32_e32 v209, s13, v1
	v_mov_b64_e32 v[184:185], 0x1580
	v_mov_b64_e32 v[186:187], 0x157f
	v_add_u32_e32 v210, s57, v207
	v_add_u32_e32 v211, s58, v207
	v_add_u32_e32 v212, 0, v2
	s_mov_b32 s59, 0x15000
	v_add_u32_e32 v226, 0x18000, v207
	v_add_u32_e32 v227, 0x1c000, v207
	s_barrier
	s_branch .LBB0_648

.LBB0_651:
	ds_read_b128 v[130:133], v210
	ds_read_b128 v[134:137], v210 offset:1024
	ds_read_b128 v[138:141], v210 offset:2048
	ds_read_b128 v[142:145], v210 offset:3072
	ds_read_b128 v[146:149], v211
	ds_read_b128 v[150:153], v211 offset:1024
	ds_read_b128 v[154:157], v211 offset:2048
	ds_read_b128 v[158:161], v211 offset:3072
	ds_read_b128 v[162:165], v212
	ds_read_b128 v[166:169], v212 offset:1024
	ds_read_b128 v[188:191], v212 offset:2048
	ds_read_b128 v[192:195], v212 offset:3072
	ds_read_b128 v[196:199], v212 offset:4096
	ds_read_b128 v[214:217], v212 offset:5120
	ds_read_b128 v[218:221], v212 offset:6144
	ds_read_b128 v[222:225], v212 offset:7168
	s_add_i32 m0, s39, 0xc000
	s_mov_b32 s32, s32
	global_load_lds_dwordx4 v180, s[88:89]
	s_add_i32 m0, s39, 0xe000
	s_mov_b32 s32, s32
	global_load_lds_dwordx4 v182, s[88:89]
	s_waitcnt vmcnt(8)
	s_waitcnt lgkmcnt(0)
	s_barrier
	s_setprio 1
	v_mfma_f32_16x16x32_bf16 v[126:129], v[130:133], v[162:165], v[126:129]
	v_mfma_f32_16x16x32_bf16 v[62:65], v[138:141], v[162:165], v[62:65]
	v_mfma_f32_16x16x32_bf16 v[122:125], v[130:133], v[188:191], v[122:125]
	s_add_u32 s90, s88, 0x100
	v_mfma_f32_16x16x32_bf16 v[58:61], v[138:141], v[188:191], v[58:61]
	s_addc_u32 s91, s89, 0
	v_mfma_f32_16x16x32_bf16 v[110:113], v[130:133], v[196:199], v[110:113]
	s_cmp_eq_u32 s66, 60
	v_mfma_f32_16x16x32_bf16 v[50:53], v[138:141], v[196:199], v[50:53]
	s_cselect_b32 s95, s79, s91
	v_mfma_f32_16x16x32_bf16 v[106:109], v[130:133], v[218:221], v[106:109]
	s_cselect_b32 s94, s85, s90
	v_mfma_f32_16x16x32_bf16 v[42:45], v[138:141], v[218:221], v[42:45]
	s_cselect_b32 s93, s77, vcc_hi
	v_mfma_f32_16x16x32_bf16 v[126:129], v[134:137], v[166:169], v[126:129]
	s_cselect_b32 s92, s87, vcc_lo
	v_mfma_f32_16x16x32_bf16 v[62:65], v[142:145], v[166:169], v[62:65]
	s_add_u32 s98, s92, 0x100000
	v_mfma_f32_16x16x32_bf16 v[122:125], v[134:137], v[192:195], v[122:125]
	s_addc_u32 s99, s93, 0
	v_mfma_f32_16x16x32_bf16 v[58:61], v[142:145], v[192:195], v[58:61]
	s_add_u32 s100, s94, 0x100000
	v_mfma_f32_16x16x32_bf16 v[110:113], v[134:137], v[214:217], v[110:113]
	s_addc_u32 s101, s95, 0
	v_mfma_f32_16x16x32_bf16 v[50:53], v[142:145], v[214:217], v[50:53]
	v_mfma_f32_16x16x32_bf16 v[106:109], v[134:137], v[222:225], v[106:109]
	v_mfma_f32_16x16x32_bf16 v[42:45], v[142:145], v[222:225], v[42:45]
	v_mfma_f32_16x16x32_bf16 v[118:121], v[146:149], v[162:165], v[118:121]
	v_mfma_f32_16x16x32_bf16 v[54:57], v[154:157], v[162:165], v[54:57]
	v_mfma_f32_16x16x32_bf16 v[114:117], v[146:149], v[188:191], v[114:117]
	v_mfma_f32_16x16x32_bf16 v[46:49], v[154:157], v[188:191], v[46:49]
	v_mfma_f32_16x16x32_bf16 v[102:105], v[146:149], v[196:199], v[102:105]
	v_mfma_f32_16x16x32_bf16 v[38:41], v[154:157], v[196:199], v[38:41]
	v_mfma_f32_16x16x32_bf16 v[98:101], v[146:149], v[218:221], v[98:101]
	v_mfma_f32_16x16x32_bf16 v[34:37], v[154:157], v[218:221], v[34:37]
	v_mfma_f32_16x16x32_bf16 v[118:121], v[150:153], v[166:169], v[118:121]
	v_mfma_f32_16x16x32_bf16 v[54:57], v[158:161], v[166:169], v[54:57]
	v_mfma_f32_16x16x32_bf16 v[114:117], v[150:153], v[192:195], v[114:117]
	v_mfma_f32_16x16x32_bf16 v[46:49], v[158:161], v[192:195], v[46:49]
	v_mfma_f32_16x16x32_bf16 v[102:105], v[150:153], v[214:217], v[102:105]
	v_mfma_f32_16x16x32_bf16 v[38:41], v[158:161], v[214:217], v[38:41]
	v_mfma_f32_16x16x32_bf16 v[98:101], v[150:153], v[222:225], v[98:101]
	v_mfma_f32_16x16x32_bf16 v[34:37], v[158:161], v[222:225], v[34:37]
	s_setprio 0
	s_barrier
	ds_read_b128 v[162:165], v212 offset:16384
	ds_read_b128 v[166:169], v212 offset:17408
	ds_read_b128 v[188:191], v212 offset:18432
	ds_read_b128 v[192:195], v212 offset:19456
	ds_read_b128 v[196:199], v212 offset:20480
	ds_read_b128 v[214:217], v212 offset:21504
	ds_read_b128 v[218:221], v212 offset:22528
	ds_read_b128 v[222:225], v212 offset:23552
	s_add_i32 m0, s39, 0x10000
	s_mov_b32 s32, s32
	global_load_lds_dwordx4 v172, s[92:93]
	s_add_i32 m0, s39, 0x12000
	s_mov_b32 s32, s32
	global_load_lds_dwordx4 v176, s[92:93]
	s_add_i32 m0, s39, 0x14000
	s_mov_b32 s32, s32
	global_load_lds_dwordx4 v172, s[98:99]
	s_add_i32 m0, s39, 0x16000
	s_mov_b32 s32, s32
	global_load_lds_dwordx4 v176, s[98:99]
	s_mov_b32 m0, s39
	s_mov_b32 s32, s32
	global_load_lds_dwordx4 v170, s[94:95]
	s_add_i32 m0, s39, 0x2000
	s_mov_b32 s32, s32
	global_load_lds_dwordx4 v174, s[94:95]
	s_waitcnt vmcnt(8)
	s_waitcnt lgkmcnt(0)
	s_barrier
	s_setprio 1
	v_mfma_f32_16x16x32_bf16 v[94:97], v[130:133], v[162:165], v[94:97]
	v_mfma_f32_16x16x32_bf16 v[30:33], v[138:141], v[162:165], v[30:33]
	v_mfma_f32_16x16x32_bf16 v[90:93], v[130:133], v[188:191], v[90:93]
	v_mfma_f32_16x16x32_bf16 v[26:29], v[138:141], v[188:191], v[26:29]
	v_mfma_f32_16x16x32_bf16 v[82:85], v[130:133], v[196:199], v[82:85]
	v_mfma_f32_16x16x32_bf16 v[18:21], v[138:141], v[196:199], v[18:21]
	v_mfma_f32_16x16x32_bf16 v[74:77], v[130:133], v[218:221], v[74:77]
	v_mfma_f32_16x16x32_bf16 v[10:13], v[138:141], v[218:221], v[10:13]
	v_mfma_f32_16x16x32_bf16 v[94:97], v[134:137], v[166:169], v[94:97]
	v_mfma_f32_16x16x32_bf16 v[30:33], v[142:145], v[166:169], v[30:33]
	v_mfma_f32_16x16x32_bf16 v[90:93], v[134:137], v[192:195], v[90:93]
	v_mfma_f32_16x16x32_bf16 v[26:29], v[142:145], v[192:195], v[26:29]
	v_mfma_f32_16x16x32_bf16 v[82:85], v[134:137], v[214:217], v[82:85]
	v_mfma_f32_16x16x32_bf16 v[18:21], v[142:145], v[214:217], v[18:21]
	v_mfma_f32_16x16x32_bf16 v[74:77], v[134:137], v[222:225], v[74:77]
	v_mfma_f32_16x16x32_bf16 v[10:13], v[142:145], v[222:225], v[10:13]
	v_mfma_f32_16x16x32_bf16 v[86:89], v[146:149], v[162:165], v[86:89]
	v_mfma_f32_16x16x32_bf16 v[22:25], v[154:157], v[162:165], v[22:25]
	v_mfma_f32_16x16x32_bf16 v[78:81], v[146:149], v[188:191], v[78:81]
	v_mfma_f32_16x16x32_bf16 v[14:17], v[154:157], v[188:191], v[14:17]
	v_mfma_f32_16x16x32_bf16 v[70:73], v[146:149], v[196:199], v[70:73]
	v_mfma_f32_16x16x32_bf16 v[6:9], v[154:157], v[196:199], v[6:9]
	v_mfma_f32_16x16x32_bf16 v[66:69], v[146:149], v[218:221], v[66:69]
	v_mfma_f32_16x16x32_bf16 v[2:5], v[154:157], v[218:221], v[2:5]
	v_mfma_f32_16x16x32_bf16 v[86:89], v[150:153], v[166:169], v[86:89]
	v_mfma_f32_16x16x32_bf16 v[22:25], v[158:161], v[166:169], v[22:25]
	v_mfma_f32_16x16x32_bf16 v[78:81], v[150:153], v[192:195], v[78:81]
	v_mfma_f32_16x16x32_bf16 v[14:17], v[158:161], v[192:195], v[14:17]
	v_mfma_f32_16x16x32_bf16 v[70:73], v[150:153], v[214:217], v[70:73]
	v_mfma_f32_16x16x32_bf16 v[6:9], v[158:161], v[214:217], v[6:9]
	v_mfma_f32_16x16x32_bf16 v[66:69], v[150:153], v[222:225], v[66:69]
	v_mfma_f32_16x16x32_bf16 v[2:5], v[158:161], v[222:225], v[2:5]
	s_setprio 0
	s_barrier
	ds_read_b128 v[130:133], v226
	ds_read_b128 v[134:137], v226 offset:1024
	ds_read_b128 v[138:141], v226 offset:2048
	ds_read_b128 v[142:145], v226 offset:3072
	ds_read_b128 v[146:149], v227
	ds_read_b128 v[150:153], v227 offset:1024
	ds_read_b128 v[154:157], v227 offset:2048
	ds_read_b128 v[158:161], v227 offset:3072
	ds_read_b128 v[162:165], v212 offset:32768
	ds_read_b128 v[166:169], v212 offset:33792
	ds_read_b128 v[188:191], v212 offset:34816
	ds_read_b128 v[192:195], v212 offset:35840
	ds_read_b128 v[196:199], v212 offset:36864
	ds_read_b128 v[214:217], v212 offset:37888
	ds_read_b128 v[218:221], v212 offset:38912
	ds_read_b128 v[222:225], v212 offset:39936
	s_add_i32 m0, s39, 0x4000
	s_mov_b32 s32, s32
	global_load_lds_dwordx4 v170, s[100:101]
	s_add_i32 m0, s39, 0x6000
	s_mov_b32 s32, s32
	global_load_lds_dwordx4 v174, s[100:101]
	s_waitcnt vmcnt(8)
	s_waitcnt lgkmcnt(0)
	s_barrier
	s_setprio 1
	v_mfma_f32_16x16x32_bf16 v[126:129], v[130:133], v[162:165], v[126:129]
	v_mfma_f32_16x16x32_bf16 v[62:65], v[138:141], v[162:165], v[62:65]
	v_mfma_f32_16x16x32_bf16 v[122:125], v[130:133], v[188:191], v[122:125]
	v_mfma_f32_16x16x32_bf16 v[58:61], v[138:141], v[188:191], v[58:61]
	v_mfma_f32_16x16x32_bf16 v[110:113], v[130:133], v[196:199], v[110:113]
	v_mfma_f32_16x16x32_bf16 v[50:53], v[138:141], v[196:199], v[50:53]
	v_mfma_f32_16x16x32_bf16 v[106:109], v[130:133], v[218:221], v[106:109]
	v_mfma_f32_16x16x32_bf16 v[42:45], v[138:141], v[218:221], v[42:45]
	v_mfma_f32_16x16x32_bf16 v[126:129], v[134:137], v[166:169], v[126:129]
	v_mfma_f32_16x16x32_bf16 v[62:65], v[142:145], v[166:169], v[62:65]
	v_mfma_f32_16x16x32_bf16 v[122:125], v[134:137], v[192:195], v[122:125]
	v_mfma_f32_16x16x32_bf16 v[58:61], v[142:145], v[192:195], v[58:61]
	v_mfma_f32_16x16x32_bf16 v[110:113], v[134:137], v[214:217], v[110:113]
	v_mfma_f32_16x16x32_bf16 v[50:53], v[142:145], v[214:217], v[50:53]
	v_mfma_f32_16x16x32_bf16 v[106:109], v[134:137], v[222:225], v[106:109]
	v_mfma_f32_16x16x32_bf16 v[42:45], v[142:145], v[222:225], v[42:45]
	v_mfma_f32_16x16x32_bf16 v[118:121], v[146:149], v[162:165], v[118:121]
	v_mfma_f32_16x16x32_bf16 v[54:57], v[154:157], v[162:165], v[54:57]
	v_mfma_f32_16x16x32_bf16 v[114:117], v[146:149], v[188:191], v[114:117]
	v_mfma_f32_16x16x32_bf16 v[46:49], v[154:157], v[188:191], v[46:49]
	v_mfma_f32_16x16x32_bf16 v[102:105], v[146:149], v[196:199], v[102:105]
	v_mfma_f32_16x16x32_bf16 v[38:41], v[154:157], v[196:199], v[38:41]
	v_mfma_f32_16x16x32_bf16 v[98:101], v[146:149], v[218:221], v[98:101]
	v_mfma_f32_16x16x32_bf16 v[34:37], v[154:157], v[218:221], v[34:37]
	v_mfma_f32_16x16x32_bf16 v[118:121], v[150:153], v[166:169], v[118:121]
	v_mfma_f32_16x16x32_bf16 v[54:57], v[158:161], v[166:169], v[54:57]
	v_mfma_f32_16x16x32_bf16 v[114:117], v[150:153], v[192:195], v[114:117]
	v_mfma_f32_16x16x32_bf16 v[46:49], v[158:161], v[192:195], v[46:49]
	v_mfma_f32_16x16x32_bf16 v[102:105], v[150:153], v[214:217], v[102:105]
	v_mfma_f32_16x16x32_bf16 v[38:41], v[158:161], v[214:217], v[38:41]
	v_mfma_f32_16x16x32_bf16 v[98:101], v[150:153], v[222:225], v[98:101]
	v_mfma_f32_16x16x32_bf16 v[34:37], v[158:161], v[222:225], v[34:37]
	s_setprio 0
	s_barrier
	ds_read_b128 v[162:165], v212 offset:49152
	ds_read_b128 v[166:169], v212 offset:50176
	ds_read_b128 v[188:191], v212 offset:51200
	ds_read_b128 v[192:195], v212 offset:52224
	ds_read_b128 v[196:199], v212 offset:53248
	ds_read_b128 v[214:217], v212 offset:54272
	ds_read_b128 v[218:221], v212 offset:55296
	ds_read_b128 v[222:225], v212 offset:56320
	s_add_i32 m0, s39, 0x17f80
	s_mov_b32 s32, s32
	global_load_lds_dwordx4 v172, s[92:93] offset:128
	s_add_i32 m0, s39, 0x19f80
	s_mov_b32 s32, s32
	global_load_lds_dwordx4 v176, s[92:93] offset:128
	s_add_i32 m0, s39, 0x1bf80
	s_mov_b32 s32, s32
	global_load_lds_dwordx4 v172, s[98:99] offset:128
	s_add_i32 m0, s39, 0x1df80
	s_mov_b32 s32, s32
	global_load_lds_dwordx4 v176, s[98:99] offset:128
	s_add_i32 m0, s39, 0x7f80
	s_mov_b32 s32, s32
	global_load_lds_dwordx4 v170, s[94:95] offset:128
	s_add_i32 m0, s39, 0x9f80
	s_mov_b32 s32, s32
	global_load_lds_dwordx4 v174, s[94:95] offset:128
	s_waitcnt vmcnt(8)
	s_waitcnt lgkmcnt(0)
	s_barrier
	s_setprio 1
	v_mfma_f32_16x16x32_bf16 v[94:97], v[130:133], v[162:165], v[94:97]
	v_mfma_f32_16x16x32_bf16 v[30:33], v[138:141], v[162:165], v[30:33]
	v_mfma_f32_16x16x32_bf16 v[90:93], v[130:133], v[188:191], v[90:93]
	v_mfma_f32_16x16x32_bf16 v[26:29], v[138:141], v[188:191], v[26:29]
	v_mfma_f32_16x16x32_bf16 v[82:85], v[130:133], v[196:199], v[82:85]
	v_mfma_f32_16x16x32_bf16 v[18:21], v[138:141], v[196:199], v[18:21]
	v_mfma_f32_16x16x32_bf16 v[74:77], v[130:133], v[218:221], v[74:77]
	v_mfma_f32_16x16x32_bf16 v[10:13], v[138:141], v[218:221], v[10:13]
	v_mfma_f32_16x16x32_bf16 v[94:97], v[134:137], v[166:169], v[94:97]
	v_mfma_f32_16x16x32_bf16 v[30:33], v[142:145], v[166:169], v[30:33]
	v_mfma_f32_16x16x32_bf16 v[90:93], v[134:137], v[192:195], v[90:93]
	v_mfma_f32_16x16x32_bf16 v[26:29], v[142:145], v[192:195], v[26:29]
	v_mfma_f32_16x16x32_bf16 v[82:85], v[134:137], v[214:217], v[82:85]
	v_mfma_f32_16x16x32_bf16 v[18:21], v[142:145], v[214:217], v[18:21]
	v_mfma_f32_16x16x32_bf16 v[74:77], v[134:137], v[222:225], v[74:77]
	v_mfma_f32_16x16x32_bf16 v[10:13], v[142:145], v[222:225], v[10:13]
	v_mfma_f32_16x16x32_bf16 v[86:89], v[146:149], v[162:165], v[86:89]
	v_mfma_f32_16x16x32_bf16 v[22:25], v[154:157], v[162:165], v[22:25]
	v_mfma_f32_16x16x32_bf16 v[78:81], v[146:149], v[188:191], v[78:81]
	v_mfma_f32_16x16x32_bf16 v[14:17], v[154:157], v[188:191], v[14:17]
	v_mfma_f32_16x16x32_bf16 v[70:73], v[146:149], v[196:199], v[70:73]
	v_mfma_f32_16x16x32_bf16 v[6:9], v[154:157], v[196:199], v[6:9]
	v_mfma_f32_16x16x32_bf16 v[66:69], v[146:149], v[218:221], v[66:69]
	v_mfma_f32_16x16x32_bf16 v[2:5], v[154:157], v[218:221], v[2:5]
	v_mfma_f32_16x16x32_bf16 v[86:89], v[150:153], v[166:169], v[86:89]
	v_mfma_f32_16x16x32_bf16 v[22:25], v[158:161], v[166:169], v[22:25]
	v_mfma_f32_16x16x32_bf16 v[78:81], v[150:153], v[192:195], v[78:81]
	s_add_i32 s66, s66, 2
	v_mfma_f32_16x16x32_bf16 v[14:17], v[158:161], v[192:195], v[14:17]
	s_add_u32 vcc_lo, vcc_lo, 0x100
	v_mfma_f32_16x16x32_bf16 v[70:73], v[150:153], v[214:217], v[70:73]
	s_addc_u32 vcc_hi, vcc_hi, 0
	v_mfma_f32_16x16x32_bf16 v[6:9], v[158:161], v[214:217], v[6:9]
	s_mov_b64 s[88:89], s[90:91]
	v_mfma_f32_16x16x32_bf16 v[66:69], v[150:153], v[222:225], v[66:69]
	s_cmp_gt_u32 s66, 61
	v_mfma_f32_16x16x32_bf16 v[2:5], v[158:161], v[222:225], v[2:5]
	s_setprio 0
	s_barrier
	s_cbranch_scc0 .LBB0_651
	s_and_b64 vcc, exec, s[36:37]
	s_cbranch_vccz .LBB0_654
	s_barrier

.LBB0_834:
	ds_read_b128 v[146:149], v152
	ds_read_b128 v[156:159], v152 offset:1024
	ds_read_b128 v[160:163], v152 offset:2048
	ds_read_b128 v[164:167], v152 offset:3072
	ds_read_b128 v[168:171], v153
	ds_read_b128 v[172:175], v153 offset:1024
	ds_read_b128 v[176:179], v153 offset:2048
	ds_read_b128 v[180:183], v153 offset:3072
	s_add_u32 s34, s42, 0x1fc000
	s_addc_u32 s44, s43, 0
	s_cmpk_eq_i32 s61, 0xa8
	s_cselect_b32 s48, s41, s34
	s_cselect_b32 s49, s23, s44
	s_cselect_b32 s47, s21, s60
	s_cselect_b32 s46, s58, s59
	s_add_u32 s44, s48, 0x200000
	s_addc_u32 s45, s49, 0
	s_add_i32 m0, s1, 0xc000
	ds_read_b128 v[184:187], v154
	ds_read_b128 v[188:191], v154 offset:1024
	ds_read_b128 v[192:195], v154 offset:2048
	ds_read_b128 v[196:199], v154 offset:3072
	ds_read_b128 v[206:209], v154 offset:4096
	ds_read_b128 v[210:213], v154 offset:5120
	ds_read_b128 v[214:217], v154 offset:6144
	ds_read_b128 v[218:221], v154 offset:7168
	global_load_lds_dwordx4 v138, s[42:43]
	s_add_i32 m0, s1, 0xe000
	s_mov_b32 s32, s32
	global_load_lds_dwordx4 v140, s[42:43]
	s_waitcnt vmcnt(8)
	s_waitcnt lgkmcnt(0)
	s_barrier
	s_setprio 1
	s_waitcnt lgkmcnt(0)
	v_mfma_f32_16x16x32_bf16 v[126:129], v[146:149], v[184:187], v[126:129]
	v_mfma_f32_16x16x32_bf16 v[122:125], v[160:163], v[184:187], v[122:125]
	v_mfma_f32_16x16x32_bf16 v[110:113], v[146:149], v[192:195], v[110:113]
	v_mfma_f32_16x16x32_bf16 v[106:109], v[160:163], v[192:195], v[106:109]
	v_mfma_f32_16x16x32_bf16 v[94:97], v[146:149], v[206:209], v[94:97]
	v_mfma_f32_16x16x32_bf16 v[90:93], v[160:163], v[206:209], v[90:93]
	v_mfma_f32_16x16x32_bf16 v[78:81], v[146:149], v[214:217], v[78:81]
	v_mfma_f32_16x16x32_bf16 v[74:77], v[160:163], v[214:217], v[74:77]
	v_mfma_f32_16x16x32_bf16 v[126:129], v[156:159], v[188:191], v[126:129]
	v_mfma_f32_16x16x32_bf16 v[122:125], v[164:167], v[188:191], v[122:125]
	v_mfma_f32_16x16x32_bf16 v[110:113], v[156:159], v[196:199], v[110:113]
	v_mfma_f32_16x16x32_bf16 v[106:109], v[164:167], v[196:199], v[106:109]
	v_mfma_f32_16x16x32_bf16 v[94:97], v[156:159], v[210:213], v[94:97]
	v_mfma_f32_16x16x32_bf16 v[90:93], v[164:167], v[210:213], v[90:93]
	v_mfma_f32_16x16x32_bf16 v[78:81], v[156:159], v[218:221], v[78:81]
	v_mfma_f32_16x16x32_bf16 v[74:77], v[164:167], v[218:221], v[74:77]
	s_setprio 0
	s_setprio 1
	v_mfma_f32_16x16x32_bf16 v[118:121], v[168:171], v[184:187], v[118:121]
	v_mfma_f32_16x16x32_bf16 v[114:117], v[176:179], v[184:187], v[114:117]
	v_mfma_f32_16x16x32_bf16 v[102:105], v[168:171], v[192:195], v[102:105]
	v_mfma_f32_16x16x32_bf16 v[98:101], v[176:179], v[192:195], v[98:101]
	v_mfma_f32_16x16x32_bf16 v[86:89], v[168:171], v[206:209], v[86:89]
	v_mfma_f32_16x16x32_bf16 v[82:85], v[176:179], v[206:209], v[82:85]
	v_mfma_f32_16x16x32_bf16 v[70:73], v[168:171], v[214:217], v[70:73]
	v_mfma_f32_16x16x32_bf16 v[66:69], v[176:179], v[214:217], v[66:69]
	v_mfma_f32_16x16x32_bf16 v[118:121], v[172:175], v[188:191], v[118:121]
	v_mfma_f32_16x16x32_bf16 v[114:117], v[180:183], v[188:191], v[114:117]
	v_mfma_f32_16x16x32_bf16 v[102:105], v[172:175], v[196:199], v[102:105]
	v_mfma_f32_16x16x32_bf16 v[98:101], v[180:183], v[196:199], v[98:101]
	v_mfma_f32_16x16x32_bf16 v[86:89], v[172:175], v[210:213], v[86:89]
	v_mfma_f32_16x16x32_bf16 v[82:85], v[180:183], v[210:213], v[82:85]
	v_mfma_f32_16x16x32_bf16 v[70:73], v[172:175], v[218:221], v[70:73]
	v_mfma_f32_16x16x32_bf16 v[66:69], v[180:183], v[218:221], v[66:69]
	s_setprio 0
	s_barrier
	s_add_i32 s34, s55, s0
	s_mov_b32 m0, s34
	ds_read_b128 v[184:187], v154 offset:16384
	ds_read_b128 v[188:191], v154 offset:17408
	ds_read_b128 v[192:195], v154 offset:18432
	ds_read_b128 v[196:199], v154 offset:19456
	ds_read_b128 v[206:209], v154 offset:20480
	ds_read_b128 v[210:213], v154 offset:21504
	ds_read_b128 v[214:217], v154 offset:22528
	ds_read_b128 v[218:221], v154 offset:23552
	global_load_lds_dwordx4 v132, s[46:47]
	s_add_i32 m0, s34, 0x2000
	s_add_u32 s62, s46, 0x4000
	s_addc_u32 s63, s47, 0
	s_add_i32 s34, s56, s0
	global_load_lds_dwordx4 v136, s[46:47]
	s_mov_b32 m0, s34
	s_mov_b32 s32, s32
	global_load_lds_dwordx4 v132, s[62:63]
	s_add_i32 m0, s34, 0x2000
	s_mov_b32 s32, s32
	global_load_lds_dwordx4 v136, s[62:63]
	s_mov_b32 m0, s1
	s_mov_b32 s32, s32
	global_load_lds_dwordx4 v130, s[48:49]
	s_mov_b32 m0, s3
	s_mov_b32 s32, s32
	global_load_lds_dwordx4 v134, s[48:49]
	s_waitcnt vmcnt(8)
	s_waitcnt lgkmcnt(0)
	s_barrier
	s_setprio 1
	s_waitcnt lgkmcnt(0)
	v_mfma_f32_16x16x32_bf16 v[62:65], v[146:149], v[184:187], v[62:65]
	v_mfma_f32_16x16x32_bf16 v[58:61], v[160:163], v[184:187], v[58:61]
	v_mfma_f32_16x16x32_bf16 v[46:49], v[146:149], v[192:195], v[46:49]
	v_mfma_f32_16x16x32_bf16 v[42:45], v[160:163], v[192:195], v[42:45]
	v_mfma_f32_16x16x32_bf16 v[30:33], v[146:149], v[206:209], v[30:33]
	v_mfma_f32_16x16x32_bf16 v[26:29], v[160:163], v[206:209], v[26:29]
	v_mfma_f32_16x16x32_bf16 v[14:17], v[146:149], v[214:217], v[14:17]
	v_mfma_f32_16x16x32_bf16 v[10:13], v[160:163], v[214:217], v[10:13]
	v_mfma_f32_16x16x32_bf16 v[62:65], v[156:159], v[188:191], v[62:65]
	v_mfma_f32_16x16x32_bf16 v[58:61], v[164:167], v[188:191], v[58:61]
	v_mfma_f32_16x16x32_bf16 v[46:49], v[156:159], v[196:199], v[46:49]
	v_mfma_f32_16x16x32_bf16 v[42:45], v[164:167], v[196:199], v[42:45]
	v_mfma_f32_16x16x32_bf16 v[30:33], v[156:159], v[210:213], v[30:33]
	v_mfma_f32_16x16x32_bf16 v[26:29], v[164:167], v[210:213], v[26:29]
	v_mfma_f32_16x16x32_bf16 v[14:17], v[156:159], v[218:221], v[14:17]
	v_mfma_f32_16x16x32_bf16 v[10:13], v[164:167], v[218:221], v[10:13]
	s_setprio 0
	s_setprio 1
	v_mfma_f32_16x16x32_bf16 v[54:57], v[168:171], v[184:187], v[54:57]
	v_mfma_f32_16x16x32_bf16 v[50:53], v[176:179], v[184:187], v[50:53]
	v_mfma_f32_16x16x32_bf16 v[38:41], v[168:171], v[192:195], v[38:41]
	v_mfma_f32_16x16x32_bf16 v[34:37], v[176:179], v[192:195], v[34:37]
	v_mfma_f32_16x16x32_bf16 v[22:25], v[168:171], v[206:209], v[22:25]
	v_mfma_f32_16x16x32_bf16 v[18:21], v[176:179], v[206:209], v[18:21]
	v_mfma_f32_16x16x32_bf16 v[6:9], v[168:171], v[214:217], v[6:9]
	v_mfma_f32_16x16x32_bf16 v[2:5], v[176:179], v[214:217], v[2:5]
	v_mfma_f32_16x16x32_bf16 v[54:57], v[172:175], v[188:191], v[54:57]
	v_mfma_f32_16x16x32_bf16 v[50:53], v[180:183], v[188:191], v[50:53]
	v_mfma_f32_16x16x32_bf16 v[38:41], v[172:175], v[196:199], v[38:41]
	v_mfma_f32_16x16x32_bf16 v[34:37], v[180:183], v[196:199], v[34:37]
	v_mfma_f32_16x16x32_bf16 v[22:25], v[172:175], v[210:213], v[22:25]
	v_mfma_f32_16x16x32_bf16 v[18:21], v[180:183], v[210:213], v[18:21]
	v_mfma_f32_16x16x32_bf16 v[6:9], v[172:175], v[218:221], v[6:9]
	v_mfma_f32_16x16x32_bf16 v[2:5], v[180:183], v[218:221], v[2:5]
	s_setprio 0
	s_barrier
	s_add_i32 s34, 0, 0x18000
	v_add_u32_e32 v155, s34, v150
	s_add_i32 s62, 0, 0x1c000
	ds_read_b128 v[146:149], v155
	ds_read_b128 v[156:159], v155 offset:1024
	ds_read_b128 v[160:163], v155 offset:2048
	ds_read_b128 v[164:167], v155 offset:3072
	v_add_u32_e32 v155, s62, v150
	ds_read_b128 v[168:171], v155
	ds_read_b128 v[172:175], v155 offset:1024
	ds_read_b128 v[176:179], v155 offset:2048
	ds_read_b128 v[180:183], v155 offset:3072
	s_add_u32 s48, s48, 0x4000
	s_addc_u32 s49, s49, 0
	s_mov_b32 m0, s33
	ds_read_b128 v[184:187], v154 offset:32768
	ds_read_b128 v[188:191], v154 offset:33792
	ds_read_b128 v[192:195], v154 offset:34816
	ds_read_b128 v[196:199], v154 offset:35840
	ds_read_b128 v[206:209], v154 offset:36864
	ds_read_b128 v[210:213], v154 offset:37888
	ds_read_b128 v[214:217], v154 offset:38912
	ds_read_b128 v[218:221], v154 offset:39936
	global_load_lds_dwordx4 v130, s[48:49]
	s_mov_b32 m0, s35
	s_mov_b32 s32, s32
	global_load_lds_dwordx4 v134, s[48:49]
	s_waitcnt vmcnt(8)
	s_waitcnt lgkmcnt(0)
	s_barrier
	s_setprio 1
	s_waitcnt lgkmcnt(0)
	v_mfma_f32_16x16x32_bf16 v[126:129], v[146:149], v[184:187], v[126:129]
	v_mfma_f32_16x16x32_bf16 v[122:125], v[160:163], v[184:187], v[122:125]
	v_mfma_f32_16x16x32_bf16 v[110:113], v[146:149], v[192:195], v[110:113]
	v_mfma_f32_16x16x32_bf16 v[106:109], v[160:163], v[192:195], v[106:109]
	v_mfma_f32_16x16x32_bf16 v[94:97], v[146:149], v[206:209], v[94:97]
	v_mfma_f32_16x16x32_bf16 v[90:93], v[160:163], v[206:209], v[90:93]
	v_mfma_f32_16x16x32_bf16 v[78:81], v[146:149], v[214:217], v[78:81]
	v_mfma_f32_16x16x32_bf16 v[74:77], v[160:163], v[214:217], v[74:77]
	v_mfma_f32_16x16x32_bf16 v[126:129], v[156:159], v[188:191], v[126:129]
	v_mfma_f32_16x16x32_bf16 v[122:125], v[164:167], v[188:191], v[122:125]
	v_mfma_f32_16x16x32_bf16 v[110:113], v[156:159], v[196:199], v[110:113]
	v_mfma_f32_16x16x32_bf16 v[106:109], v[164:167], v[196:199], v[106:109]
	v_mfma_f32_16x16x32_bf16 v[94:97], v[156:159], v[210:213], v[94:97]
	v_mfma_f32_16x16x32_bf16 v[90:93], v[164:167], v[210:213], v[90:93]
	v_mfma_f32_16x16x32_bf16 v[78:81], v[156:159], v[218:221], v[78:81]
	v_mfma_f32_16x16x32_bf16 v[74:77], v[164:167], v[218:221], v[74:77]
	s_setprio 0
	s_setprio 1
	v_mfma_f32_16x16x32_bf16 v[118:121], v[168:171], v[184:187], v[118:121]
	v_mfma_f32_16x16x32_bf16 v[114:117], v[176:179], v[184:187], v[114:117]
	v_mfma_f32_16x16x32_bf16 v[102:105], v[168:171], v[192:195], v[102:105]
	v_mfma_f32_16x16x32_bf16 v[98:101], v[176:179], v[192:195], v[98:101]
	v_mfma_f32_16x16x32_bf16 v[86:89], v[168:171], v[206:209], v[86:89]
	v_mfma_f32_16x16x32_bf16 v[82:85], v[176:179], v[206:209], v[82:85]
	v_mfma_f32_16x16x32_bf16 v[70:73], v[168:171], v[214:217], v[70:73]
	v_mfma_f32_16x16x32_bf16 v[66:69], v[176:179], v[214:217], v[66:69]
	v_mfma_f32_16x16x32_bf16 v[118:121], v[172:175], v[188:191], v[118:121]
	v_mfma_f32_16x16x32_bf16 v[114:117], v[180:183], v[188:191], v[114:117]
	v_mfma_f32_16x16x32_bf16 v[102:105], v[172:175], v[196:199], v[102:105]
	v_mfma_f32_16x16x32_bf16 v[98:101], v[180:183], v[196:199], v[98:101]
	v_mfma_f32_16x16x32_bf16 v[86:89], v[172:175], v[210:213], v[86:89]
	v_mfma_f32_16x16x32_bf16 v[82:85], v[180:183], v[210:213], v[82:85]
	v_mfma_f32_16x16x32_bf16 v[70:73], v[172:175], v[218:221], v[70:73]
	v_mfma_f32_16x16x32_bf16 v[66:69], v[180:183], v[218:221], v[66:69]
	s_setprio 0
	s_barrier
	s_add_u32 s48, s46, 0x80000
	s_addc_u32 s49, s47, 0
	s_add_i32 s34, s34, s0
	s_mov_b32 m0, s34
	ds_read_b128 v[184:187], v154 offset:49152
	ds_read_b128 v[188:191], v154 offset:50176
	ds_read_b128 v[192:195], v154 offset:51200
	ds_read_b128 v[196:199], v154 offset:52224
	ds_read_b128 v[206:209], v154 offset:53248
	ds_read_b128 v[210:213], v154 offset:54272
	ds_read_b128 v[214:217], v154 offset:55296
	ds_read_b128 v[218:221], v154 offset:56320
	global_load_lds_dwordx4 v132, s[48:49]
	s_add_i32 m0, s34, 0x2000
	s_add_u32 s46, s46, 0x84000
	s_addc_u32 s47, s47, 0
	s_add_i32 s34, s62, s0
	global_load_lds_dwordx4 v136, s[48:49]
	s_mov_b32 m0, s34
	s_mov_b32 s32, s32
	global_load_lds_dwordx4 v132, s[46:47]
	s_add_i32 m0, s34, 0x2000
	s_mov_b32 s32, s32
	global_load_lds_dwordx4 v136, s[46:47]
	s_mov_b32 m0, s51
	s_mov_b32 s32, s32
	global_load_lds_dwordx4 v130, s[44:45]
	s_mov_b32 m0, s52
	s_mov_b32 s32, s32
	global_load_lds_dwordx4 v134, s[44:45]
	s_waitcnt vmcnt(8)
	s_waitcnt lgkmcnt(0)
	s_barrier
	s_setprio 1
	s_waitcnt lgkmcnt(0)
	v_mfma_f32_16x16x32_bf16 v[62:65], v[146:149], v[184:187], v[62:65]
	v_mfma_f32_16x16x32_bf16 v[58:61], v[160:163], v[184:187], v[58:61]
	v_mfma_f32_16x16x32_bf16 v[46:49], v[146:149], v[192:195], v[46:49]
	v_mfma_f32_16x16x32_bf16 v[42:45], v[160:163], v[192:195], v[42:45]
	v_mfma_f32_16x16x32_bf16 v[30:33], v[146:149], v[206:209], v[30:33]
	v_mfma_f32_16x16x32_bf16 v[26:29], v[160:163], v[206:209], v[26:29]
	v_mfma_f32_16x16x32_bf16 v[14:17], v[146:149], v[214:217], v[14:17]
	v_mfma_f32_16x16x32_bf16 v[10:13], v[160:163], v[214:217], v[10:13]
	v_mfma_f32_16x16x32_bf16 v[62:65], v[156:159], v[188:191], v[62:65]
	v_mfma_f32_16x16x32_bf16 v[58:61], v[164:167], v[188:191], v[58:61]
	v_mfma_f32_16x16x32_bf16 v[46:49], v[156:159], v[196:199], v[46:49]
	v_mfma_f32_16x16x32_bf16 v[42:45], v[164:167], v[196:199], v[42:45]
	v_mfma_f32_16x16x32_bf16 v[30:33], v[156:159], v[210:213], v[30:33]
	v_mfma_f32_16x16x32_bf16 v[26:29], v[164:167], v[210:213], v[26:29]
	v_mfma_f32_16x16x32_bf16 v[14:17], v[156:159], v[218:221], v[14:17]
	v_mfma_f32_16x16x32_bf16 v[10:13], v[164:167], v[218:221], v[10:13]
	s_setprio 0
	s_setprio 1
	v_mfma_f32_16x16x32_bf16 v[54:57], v[168:171], v[184:187], v[54:57]
	v_mfma_f32_16x16x32_bf16 v[50:53], v[176:179], v[184:187], v[50:53]
	v_mfma_f32_16x16x32_bf16 v[38:41], v[168:171], v[192:195], v[38:41]
	v_mfma_f32_16x16x32_bf16 v[34:37], v[176:179], v[192:195], v[34:37]
	v_mfma_f32_16x16x32_bf16 v[22:25], v[168:171], v[206:209], v[22:25]
	v_mfma_f32_16x16x32_bf16 v[18:21], v[176:179], v[206:209], v[18:21]
	v_mfma_f32_16x16x32_bf16 v[6:9], v[168:171], v[214:217], v[6:9]
	v_mfma_f32_16x16x32_bf16 v[2:5], v[176:179], v[214:217], v[2:5]
	v_mfma_f32_16x16x32_bf16 v[54:57], v[172:175], v[188:191], v[54:57]
	v_mfma_f32_16x16x32_bf16 v[50:53], v[180:183], v[188:191], v[50:53]
	v_mfma_f32_16x16x32_bf16 v[38:41], v[172:175], v[196:199], v[38:41]
	v_mfma_f32_16x16x32_bf16 v[34:37], v[180:183], v[196:199], v[34:37]
	v_mfma_f32_16x16x32_bf16 v[22:25], v[172:175], v[210:213], v[22:25]
	v_mfma_f32_16x16x32_bf16 v[18:21], v[180:183], v[210:213], v[18:21]
	v_mfma_f32_16x16x32_bf16 v[6:9], v[172:175], v[218:221], v[6:9]
	v_mfma_f32_16x16x32_bf16 v[2:5], v[180:183], v[218:221], v[2:5]
	s_setprio 0
	s_barrier
	s_add_i32 s61, s61, 2
	s_add_u32 s59, s59, 0x100000
	s_addc_u32 s60, s60, 0
	s_add_u32 s42, s42, 0x400000
	s_addc_u32 s43, s43, 0
	s_cmpk_gt_u32 s61, 0xa9
	s_cbranch_scc0 .LBB0_834
	s_and_b64 vcc, exec, s[18:19]
	s_cbranch_vccz .LBB0_837
	s_barrier
